# phase0 layer-0 row norm also software-pipelined (three rows in flight per wave)
# baseline (speedup 1.0000x reference)
.LBB0_80:
	s_or_b64 exec, exec, s[6:7]
	v_mov_b32_e32 v0, v196
	v_mov_b32_e32 v1, v196
	v_readlane_b32 s4, v249, 0
	v_ashrrev_i32_e32 v1, 6, v1
	s_lshl_b32 s4, s4, 2
	v_writelane_b32 v249, s4, 5
	v_readlane_b32 s40, v249, 1
	s_nop 0
	s_cmpk_lg_u32 s40, 0x200
	s_cbranch_scc1 .Lnrm_p0_orig
	v_readlane_b32 s40, v249, 5
	v_lshrrev_b32_e32 v68, 6, v196
	s_load_dwordx4 s[28:31], s[84:85], 0x0
	s_load_dwordx2 s[38:39], s[84:85], 0x138
	v_mov_b32_e32 v82, 0x358637bd
	s_load_dwordx2 s[32:33], s[84:85], 0x48
	v_and_b32_e32 v69, 63, v196
	v_readfirstlane_b32 s41, v68
	v_lshlrev_b32_e32 v70, 4, v69
	v_lshlrev_b32_e32 v71, 3, v69
	s_add_i32 s40, s40, s41
	s_waitcnt lgkmcnt(0)
	global_load_dwordx4 v[4:7], v70, s[32:33]
	global_load_dwordx4 v[8:11], v70, s[32:33] offset:1024
	global_load_dwordx4 v[12:15], v70, s[32:33] offset:2048
	global_load_dwordx4 v[16:19], v70, s[32:33] offset:3072
	s_lshl_b32 s42, s40, 12
	s_add_u32 s34, s28, s42
	s_addc_u32 s35, s29, 0
	s_lshl_b32 s42, s40, 11
	s_add_u32 s36, s38, s42
	s_addc_u32 s37, s39, 0
	global_load_dwordx4 v[20:23], v70, s[34:35]
	global_load_dwordx4 v[24:27], v70, s[34:35] offset:1024
	global_load_dwordx4 v[28:31], v70, s[34:35] offset:2048
	global_load_dwordx4 v[32:35], v70, s[34:35] offset:3072
	s_add_u32 s34, s34, 0x800000
	s_addc_u32 s35, s35, 0
	global_load_dwordx4 v[36:39], v70, s[34:35]
	global_load_dwordx4 v[40:43], v70, s[34:35] offset:1024
	global_load_dwordx4 v[44:47], v70, s[34:35] offset:2048
	global_load_dwordx4 v[48:51], v70, s[34:35] offset:3072
	s_add_u32 s34, s34, 0x800000
	s_addc_u32 s35, s35, 0
	global_load_dwordx4 v[52:55], v70, s[34:35]
	global_load_dwordx4 v[56:59], v70, s[34:35] offset:1024
	global_load_dwordx4 v[60:63], v70, s[34:35] offset:2048
	global_load_dwordx4 v[64:67], v70, s[34:35] offset:3072
	s_add_u32 s34, s34, 0x800000
	s_addc_u32 s35, s35, 0
	s_waitcnt vmcnt(8)
	v_mul_f32_e32 v72, v20, v20
	v_mul_f32_e32 v73, v21, v21
	v_fmac_f32_e32 v72, v22, v22
	v_fmac_f32_e32 v73, v23, v23
	v_fmac_f32_e32 v72, v24, v24
	v_fmac_f32_e32 v73, v25, v25
	v_fmac_f32_e32 v72, v26, v26
	v_fmac_f32_e32 v73, v27, v27
	v_fmac_f32_e32 v72, v28, v28
	v_fmac_f32_e32 v73, v29, v29
	v_fmac_f32_e32 v72, v30, v30
	v_fmac_f32_e32 v73, v31, v31
	v_fmac_f32_e32 v72, v32, v32
	v_fmac_f32_e32 v73, v33, v33
	v_fmac_f32_e32 v72, v34, v34
	v_fmac_f32_e32 v73, v35, v35
	v_add_f32_e32 v72, v72, v73
	s_nop 1
	v_add_f32_dpp v72, v72, v72 quad_perm:[1,0,3,2] row_mask:0xf bank_mask:0xf
	s_nop 1
	v_add_f32_dpp v72, v72, v72 quad_perm:[2,3,0,1] row_mask:0xf bank_mask:0xf
	s_nop 1
	v_add_f32_dpp v72, v72, v72 row_half_mirror row_mask:0xf bank_mask:0xf
	s_nop 1
	v_add_f32_dpp v72, v72, v72 row_mirror row_mask:0xf bank_mask:0xf
	s_nop 1
	v_add_f32_dpp v72, v72, v72 row_bcast:15 row_mask:0xa bank_mask:0xf
	s_nop 1
	v_add_f32_dpp v72, v72, v72 row_bcast:31 row_mask:0xc bank_mask:0xf
	s_nop 1
	v_readlane_b32 s43, v72, 63
	s_nop 1
	v_mov_b32_e32 v72, s43
	v_fmamk_f32 v72, v72, 0x3a800000, v82
	v_rsq_f32_e32 v72, v72
	s_nop 0
	v_mul_f32_e32 v20, v20, v72
	v_mul_f32_e32 v21, v21, v72
	v_mul_f32_e32 v22, v22, v72
	v_mul_f32_e32 v23, v23, v72
	v_mul_f32_e32 v20, v4, v20
	v_mul_f32_e32 v21, v5, v21
	v_mul_f32_e32 v22, v6, v22
	v_mul_f32_e32 v23, v7, v23
	v_cvt_pk_bf16_f32 v74, v20, v21
	v_cvt_pk_bf16_f32 v75, v22, v23
	global_store_dwordx2 v71, v[74:75], s[36:37]
	v_mul_f32_e32 v24, v24, v72
	v_mul_f32_e32 v25, v25, v72
	v_mul_f32_e32 v26, v26, v72
	v_mul_f32_e32 v27, v27, v72
	v_mul_f32_e32 v24, v8, v24
	v_mul_f32_e32 v25, v9, v25
	v_mul_f32_e32 v26, v10, v26
	v_mul_f32_e32 v27, v11, v27
	v_cvt_pk_bf16_f32 v76, v24, v25
	v_cvt_pk_bf16_f32 v77, v26, v27
	global_store_dwordx2 v71, v[76:77], s[36:37] offset:512
	v_mul_f32_e32 v28, v28, v72
	v_mul_f32_e32 v29, v29, v72
	v_mul_f32_e32 v30, v30, v72
	v_mul_f32_e32 v31, v31, v72
	v_mul_f32_e32 v28, v12, v28
	v_mul_f32_e32 v29, v13, v29
	v_mul_f32_e32 v30, v14, v30
	v_mul_f32_e32 v31, v15, v31
	v_cvt_pk_bf16_f32 v78, v28, v29
	v_cvt_pk_bf16_f32 v79, v30, v31
	global_store_dwordx2 v71, v[78:79], s[36:37] offset:1024
	v_mul_f32_e32 v32, v32, v72
	v_mul_f32_e32 v33, v33, v72
	v_mul_f32_e32 v34, v34, v72
	v_mul_f32_e32 v35, v35, v72
	v_mul_f32_e32 v32, v16, v32
	v_mul_f32_e32 v33, v17, v33
	v_mul_f32_e32 v34, v18, v34
	v_mul_f32_e32 v35, v19, v35
	v_cvt_pk_bf16_f32 v80, v32, v33
	v_cvt_pk_bf16_f32 v81, v34, v35
	global_store_dwordx2 v71, v[80:81], s[36:37] offset:1536
	s_add_u32 s36, s36, 0x400000
	s_addc_u32 s37, s37, 0
	global_load_dwordx4 v[20:23], v70, s[34:35]
	global_load_dwordx4 v[24:27], v70, s[34:35] offset:1024
	global_load_dwordx4 v[28:31], v70, s[34:35] offset:2048
	global_load_dwordx4 v[32:35], v70, s[34:35] offset:3072
	s_add_u32 s34, s34, 0x800000
	s_addc_u32 s35, s35, 0
	s_waitcnt vmcnt(12)
	v_mul_f32_e32 v72, v36, v36
	v_mul_f32_e32 v73, v37, v37
	v_fmac_f32_e32 v72, v38, v38
	v_fmac_f32_e32 v73, v39, v39
	v_fmac_f32_e32 v72, v40, v40
	v_fmac_f32_e32 v73, v41, v41
	v_fmac_f32_e32 v72, v42, v42
	v_fmac_f32_e32 v73, v43, v43
	v_fmac_f32_e32 v72, v44, v44
	v_fmac_f32_e32 v73, v45, v45
	v_fmac_f32_e32 v72, v46, v46
	v_fmac_f32_e32 v73, v47, v47
	v_fmac_f32_e32 v72, v48, v48
	v_fmac_f32_e32 v73, v49, v49
	v_fmac_f32_e32 v72, v50, v50
	v_fmac_f32_e32 v73, v51, v51
	v_add_f32_e32 v72, v72, v73
	s_nop 1
	v_add_f32_dpp v72, v72, v72 quad_perm:[1,0,3,2] row_mask:0xf bank_mask:0xf
	s_nop 1
	v_add_f32_dpp v72, v72, v72 quad_perm:[2,3,0,1] row_mask:0xf bank_mask:0xf
	s_nop 1
	v_add_f32_dpp v72, v72, v72 row_half_mirror row_mask:0xf bank_mask:0xf
	s_nop 1
	v_add_f32_dpp v72, v72, v72 row_mirror row_mask:0xf bank_mask:0xf
	s_nop 1
	v_add_f32_dpp v72, v72, v72 row_bcast:15 row_mask:0xa bank_mask:0xf
	s_nop 1
	v_add_f32_dpp v72, v72, v72 row_bcast:31 row_mask:0xc bank_mask:0xf
	s_nop 1
	v_readlane_b32 s43, v72, 63
	s_nop 1
	v_mov_b32_e32 v72, s43
	v_fmamk_f32 v72, v72, 0x3a800000, v82
	v_rsq_f32_e32 v72, v72
	s_nop 0
	v_mul_f32_e32 v36, v36, v72
	v_mul_f32_e32 v37, v37, v72
	v_mul_f32_e32 v38, v38, v72
	v_mul_f32_e32 v39, v39, v72
	v_mul_f32_e32 v36, v4, v36
	v_mul_f32_e32 v37, v5, v37
	v_mul_f32_e32 v38, v6, v38
	v_mul_f32_e32 v39, v7, v39
	v_cvt_pk_bf16_f32 v74, v36, v37
	v_cvt_pk_bf16_f32 v75, v38, v39
	global_store_dwordx2 v71, v[74:75], s[36:37]
	v_mul_f32_e32 v40, v40, v72
	v_mul_f32_e32 v41, v41, v72
	v_mul_f32_e32 v42, v42, v72
	v_mul_f32_e32 v43, v43, v72
	v_mul_f32_e32 v40, v8, v40
	v_mul_f32_e32 v41, v9, v41
	v_mul_f32_e32 v42, v10, v42
	v_mul_f32_e32 v43, v11, v43
	v_cvt_pk_bf16_f32 v76, v40, v41
	v_cvt_pk_bf16_f32 v77, v42, v43
	global_store_dwordx2 v71, v[76:77], s[36:37] offset:512
	v_mul_f32_e32 v44, v44, v72
	v_mul_f32_e32 v45, v45, v72
	v_mul_f32_e32 v46, v46, v72
	v_mul_f32_e32 v47, v47, v72
	v_mul_f32_e32 v44, v12, v44
	v_mul_f32_e32 v45, v13, v45
	v_mul_f32_e32 v46, v14, v46
	v_mul_f32_e32 v47, v15, v47
	v_cvt_pk_bf16_f32 v78, v44, v45
	v_cvt_pk_bf16_f32 v79, v46, v47
	global_store_dwordx2 v71, v[78:79], s[36:37] offset:1024
	v_mul_f32_e32 v48, v48, v72
	v_mul_f32_e32 v49, v49, v72
	v_mul_f32_e32 v50, v50, v72
	v_mul_f32_e32 v51, v51, v72
	v_mul_f32_e32 v48, v16, v48
	v_mul_f32_e32 v49, v17, v49
	v_mul_f32_e32 v50, v18, v50
	v_mul_f32_e32 v51, v19, v51
	v_cvt_pk_bf16_f32 v80, v48, v49
	v_cvt_pk_bf16_f32 v81, v50, v51
	global_store_dwordx2 v71, v[80:81], s[36:37] offset:1536
	s_add_u32 s36, s36, 0x400000
	s_addc_u32 s37, s37, 0
	global_load_dwordx4 v[36:39], v70, s[34:35]
	global_load_dwordx4 v[40:43], v70, s[34:35] offset:1024
	global_load_dwordx4 v[44:47], v70, s[34:35] offset:2048
	global_load_dwordx4 v[48:51], v70, s[34:35] offset:3072
	s_add_u32 s34, s34, 0x800000
	s_addc_u32 s35, s35, 0
	s_waitcnt vmcnt(16)
	v_mul_f32_e32 v72, v52, v52
	v_mul_f32_e32 v73, v53, v53
	v_fmac_f32_e32 v72, v54, v54
	v_fmac_f32_e32 v73, v55, v55
	v_fmac_f32_e32 v72, v56, v56
	v_fmac_f32_e32 v73, v57, v57
	v_fmac_f32_e32 v72, v58, v58
	v_fmac_f32_e32 v73, v59, v59
	v_fmac_f32_e32 v72, v60, v60
	v_fmac_f32_e32 v73, v61, v61
	v_fmac_f32_e32 v72, v62, v62
	v_fmac_f32_e32 v73, v63, v63
	v_fmac_f32_e32 v72, v64, v64
	v_fmac_f32_e32 v73, v65, v65
	v_fmac_f32_e32 v72, v66, v66
	v_fmac_f32_e32 v73, v67, v67
	v_add_f32_e32 v72, v72, v73
	s_nop 1
	v_add_f32_dpp v72, v72, v72 quad_perm:[1,0,3,2] row_mask:0xf bank_mask:0xf
	s_nop 1
	v_add_f32_dpp v72, v72, v72 quad_perm:[2,3,0,1] row_mask:0xf bank_mask:0xf
	s_nop 1
	v_add_f32_dpp v72, v72, v72 row_half_mirror row_mask:0xf bank_mask:0xf
	s_nop 1
	v_add_f32_dpp v72, v72, v72 row_mirror row_mask:0xf bank_mask:0xf
	s_nop 1
	v_add_f32_dpp v72, v72, v72 row_bcast:15 row_mask:0xa bank_mask:0xf
	s_nop 1
	v_add_f32_dpp v72, v72, v72 row_bcast:31 row_mask:0xc bank_mask:0xf
	s_nop 1
	v_readlane_b32 s43, v72, 63
	s_nop 1
	v_mov_b32_e32 v72, s43
	v_fmamk_f32 v72, v72, 0x3a800000, v82
	v_rsq_f32_e32 v72, v72
	s_nop 0
	v_mul_f32_e32 v52, v52, v72
	v_mul_f32_e32 v53, v53, v72
	v_mul_f32_e32 v54, v54, v72
	v_mul_f32_e32 v55, v55, v72
	v_mul_f32_e32 v52, v4, v52
	v_mul_f32_e32 v53, v5, v53
	v_mul_f32_e32 v54, v6, v54
	v_mul_f32_e32 v55, v7, v55
	v_cvt_pk_bf16_f32 v74, v52, v53
	v_cvt_pk_bf16_f32 v75, v54, v55
	global_store_dwordx2 v71, v[74:75], s[36:37]
	v_mul_f32_e32 v56, v56, v72
	v_mul_f32_e32 v57, v57, v72
	v_mul_f32_e32 v58, v58, v72
	v_mul_f32_e32 v59, v59, v72
	v_mul_f32_e32 v56, v8, v56
	v_mul_f32_e32 v57, v9, v57
	v_mul_f32_e32 v58, v10, v58
	v_mul_f32_e32 v59, v11, v59
	v_cvt_pk_bf16_f32 v76, v56, v57
	v_cvt_pk_bf16_f32 v77, v58, v59
	global_store_dwordx2 v71, v[76:77], s[36:37] offset:512
	v_mul_f32_e32 v60, v60, v72
	v_mul_f32_e32 v61, v61, v72
	v_mul_f32_e32 v62, v62, v72
	v_mul_f32_e32 v63, v63, v72
	v_mul_f32_e32 v60, v12, v60
	v_mul_f32_e32 v61, v13, v61
	v_mul_f32_e32 v62, v14, v62
	v_mul_f32_e32 v63, v15, v63
	v_cvt_pk_bf16_f32 v78, v60, v61
	v_cvt_pk_bf16_f32 v79, v62, v63
	global_store_dwordx2 v71, v[78:79], s[36:37] offset:1024
	v_mul_f32_e32 v64, v64, v72
	v_mul_f32_e32 v65, v65, v72
	v_mul_f32_e32 v66, v66, v72
	v_mul_f32_e32 v67, v67, v72
	v_mul_f32_e32 v64, v16, v64
	v_mul_f32_e32 v65, v17, v65
	v_mul_f32_e32 v66, v18, v66
	v_mul_f32_e32 v67, v19, v67
	v_cvt_pk_bf16_f32 v80, v64, v65
	v_cvt_pk_bf16_f32 v81, v66, v67
	global_store_dwordx2 v71, v[80:81], s[36:37] offset:1536
	s_add_u32 s36, s36, 0x400000
	s_addc_u32 s37, s37, 0
	global_load_dwordx4 v[52:55], v70, s[34:35]
	global_load_dwordx4 v[56:59], v70, s[34:35] offset:1024
	global_load_dwordx4 v[60:63], v70, s[34:35] offset:2048
	global_load_dwordx4 v[64:67], v70, s[34:35] offset:3072
	s_add_u32 s34, s34, 0x800000
	s_addc_u32 s35, s35, 0
	s_waitcnt vmcnt(16)
	v_mul_f32_e32 v72, v20, v20
	v_mul_f32_e32 v73, v21, v21
	v_fmac_f32_e32 v72, v22, v22
	v_fmac_f32_e32 v73, v23, v23
	v_fmac_f32_e32 v72, v24, v24
	v_fmac_f32_e32 v73, v25, v25
	v_fmac_f32_e32 v72, v26, v26
	v_fmac_f32_e32 v73, v27, v27
	v_fmac_f32_e32 v72, v28, v28
	v_fmac_f32_e32 v73, v29, v29
	v_fmac_f32_e32 v72, v30, v30
	v_fmac_f32_e32 v73, v31, v31
	v_fmac_f32_e32 v72, v32, v32
	v_fmac_f32_e32 v73, v33, v33
	v_fmac_f32_e32 v72, v34, v34
	v_fmac_f32_e32 v73, v35, v35
	v_add_f32_e32 v72, v72, v73
	s_nop 1
	v_add_f32_dpp v72, v72, v72 quad_perm:[1,0,3,2] row_mask:0xf bank_mask:0xf
	s_nop 1
	v_add_f32_dpp v72, v72, v72 quad_perm:[2,3,0,1] row_mask:0xf bank_mask:0xf
	s_nop 1
	v_add_f32_dpp v72, v72, v72 row_half_mirror row_mask:0xf bank_mask:0xf
	s_nop 1
	v_add_f32_dpp v72, v72, v72 row_mirror row_mask:0xf bank_mask:0xf
	s_nop 1
	v_add_f32_dpp v72, v72, v72 row_bcast:15 row_mask:0xa bank_mask:0xf
	s_nop 1
	v_add_f32_dpp v72, v72, v72 row_bcast:31 row_mask:0xc bank_mask:0xf
	s_nop 1
	v_readlane_b32 s43, v72, 63
	s_nop 1
	v_mov_b32_e32 v72, s43
	v_fmamk_f32 v72, v72, 0x3a800000, v82
	v_rsq_f32_e32 v72, v72
	s_nop 0
	v_mul_f32_e32 v20, v20, v72
	v_mul_f32_e32 v21, v21, v72
	v_mul_f32_e32 v22, v22, v72
	v_mul_f32_e32 v23, v23, v72
	v_mul_f32_e32 v20, v4, v20
	v_mul_f32_e32 v21, v5, v21
	v_mul_f32_e32 v22, v6, v22
	v_mul_f32_e32 v23, v7, v23
	v_cvt_pk_bf16_f32 v74, v20, v21
	v_cvt_pk_bf16_f32 v75, v22, v23
	global_store_dwordx2 v71, v[74:75], s[36:37]
	v_mul_f32_e32 v24, v24, v72
	v_mul_f32_e32 v25, v25, v72
	v_mul_f32_e32 v26, v26, v72
	v_mul_f32_e32 v27, v27, v72
	v_mul_f32_e32 v24, v8, v24
	v_mul_f32_e32 v25, v9, v25
	v_mul_f32_e32 v26, v10, v26
	v_mul_f32_e32 v27, v11, v27
	v_cvt_pk_bf16_f32 v76, v24, v25
	v_cvt_pk_bf16_f32 v77, v26, v27
	global_store_dwordx2 v71, v[76:77], s[36:37] offset:512
	v_mul_f32_e32 v28, v28, v72
	v_mul_f32_e32 v29, v29, v72
	v_mul_f32_e32 v30, v30, v72
	v_mul_f32_e32 v31, v31, v72
	v_mul_f32_e32 v28, v12, v28
	v_mul_f32_e32 v29, v13, v29
	v_mul_f32_e32 v30, v14, v30
	v_mul_f32_e32 v31, v15, v31
	v_cvt_pk_bf16_f32 v78, v28, v29
	v_cvt_pk_bf16_f32 v79, v30, v31
	global_store_dwordx2 v71, v[78:79], s[36:37] offset:1024
	v_mul_f32_e32 v32, v32, v72
	v_mul_f32_e32 v33, v33, v72
	v_mul_f32_e32 v34, v34, v72
	v_mul_f32_e32 v35, v35, v72
	v_mul_f32_e32 v32, v16, v32
	v_mul_f32_e32 v33, v17, v33
	v_mul_f32_e32 v34, v18, v34
	v_mul_f32_e32 v35, v19, v35
	v_cvt_pk_bf16_f32 v80, v32, v33
	v_cvt_pk_bf16_f32 v81, v34, v35
	global_store_dwordx2 v71, v[80:81], s[36:37] offset:1536
	s_add_u32 s36, s36, 0x400000
	s_addc_u32 s37, s37, 0
	global_load_dwordx4 v[20:23], v70, s[34:35]
	global_load_dwordx4 v[24:27], v70, s[34:35] offset:1024
	global_load_dwordx4 v[28:31], v70, s[34:35] offset:2048
	global_load_dwordx4 v[32:35], v70, s[34:35] offset:3072
	s_add_u32 s34, s34, 0x800000
	s_addc_u32 s35, s35, 0
	s_waitcnt vmcnt(16)
	v_mul_f32_e32 v72, v36, v36
	v_mul_f32_e32 v73, v37, v37
	v_fmac_f32_e32 v72, v38, v38
	v_fmac_f32_e32 v73, v39, v39
	v_fmac_f32_e32 v72, v40, v40
	v_fmac_f32_e32 v73, v41, v41
	v_fmac_f32_e32 v72, v42, v42
	v_fmac_f32_e32 v73, v43, v43
	v_fmac_f32_e32 v72, v44, v44
	v_fmac_f32_e32 v73, v45, v45
	v_fmac_f32_e32 v72, v46, v46
	v_fmac_f32_e32 v73, v47, v47
	v_fmac_f32_e32 v72, v48, v48
	v_fmac_f32_e32 v73, v49, v49
	v_fmac_f32_e32 v72, v50, v50
	v_fmac_f32_e32 v73, v51, v51
	v_add_f32_e32 v72, v72, v73
	s_nop 1
	v_add_f32_dpp v72, v72, v72 quad_perm:[1,0,3,2] row_mask:0xf bank_mask:0xf
	s_nop 1
	v_add_f32_dpp v72, v72, v72 quad_perm:[2,3,0,1] row_mask:0xf bank_mask:0xf
	s_nop 1
	v_add_f32_dpp v72, v72, v72 row_half_mirror row_mask:0xf bank_mask:0xf
	s_nop 1
	v_add_f32_dpp v72, v72, v72 row_mirror row_mask:0xf bank_mask:0xf
	s_nop 1
	v_add_f32_dpp v72, v72, v72 row_bcast:15 row_mask:0xa bank_mask:0xf
	s_nop 1
	v_add_f32_dpp v72, v72, v72 row_bcast:31 row_mask:0xc bank_mask:0xf
	s_nop 1
	v_readlane_b32 s43, v72, 63
	s_nop 1
	v_mov_b32_e32 v72, s43
	v_fmamk_f32 v72, v72, 0x3a800000, v82
	v_rsq_f32_e32 v72, v72
	s_nop 0
	v_mul_f32_e32 v36, v36, v72
	v_mul_f32_e32 v37, v37, v72
	v_mul_f32_e32 v38, v38, v72
	v_mul_f32_e32 v39, v39, v72
	v_mul_f32_e32 v36, v4, v36
	v_mul_f32_e32 v37, v5, v37
	v_mul_f32_e32 v38, v6, v38
	v_mul_f32_e32 v39, v7, v39
	v_cvt_pk_bf16_f32 v74, v36, v37
	v_cvt_pk_bf16_f32 v75, v38, v39
	global_store_dwordx2 v71, v[74:75], s[36:37]
	v_mul_f32_e32 v40, v40, v72
	v_mul_f32_e32 v41, v41, v72
	v_mul_f32_e32 v42, v42, v72
	v_mul_f32_e32 v43, v43, v72
	v_mul_f32_e32 v40, v8, v40
	v_mul_f32_e32 v41, v9, v41
	v_mul_f32_e32 v42, v10, v42
	v_mul_f32_e32 v43, v11, v43
	v_cvt_pk_bf16_f32 v76, v40, v41
	v_cvt_pk_bf16_f32 v77, v42, v43
	global_store_dwordx2 v71, v[76:77], s[36:37] offset:512
	v_mul_f32_e32 v44, v44, v72
	v_mul_f32_e32 v45, v45, v72
	v_mul_f32_e32 v46, v46, v72
	v_mul_f32_e32 v47, v47, v72
	v_mul_f32_e32 v44, v12, v44
	v_mul_f32_e32 v45, v13, v45
	v_mul_f32_e32 v46, v14, v46
	v_mul_f32_e32 v47, v15, v47
	v_cvt_pk_bf16_f32 v78, v44, v45
	v_cvt_pk_bf16_f32 v79, v46, v47
	global_store_dwordx2 v71, v[78:79], s[36:37] offset:1024
	v_mul_f32_e32 v48, v48, v72
	v_mul_f32_e32 v49, v49, v72
	v_mul_f32_e32 v50, v50, v72
	v_mul_f32_e32 v51, v51, v72
	v_mul_f32_e32 v48, v16, v48
	v_mul_f32_e32 v49, v17, v49
	v_mul_f32_e32 v50, v18, v50
	v_mul_f32_e32 v51, v19, v51
	v_cvt_pk_bf16_f32 v80, v48, v49
	v_cvt_pk_bf16_f32 v81, v50, v51
	global_store_dwordx2 v71, v[80:81], s[36:37] offset:1536
	s_add_u32 s36, s36, 0x400000
	s_addc_u32 s37, s37, 0
	global_load_dwordx4 v[36:39], v70, s[34:35]
	global_load_dwordx4 v[40:43], v70, s[34:35] offset:1024
	global_load_dwordx4 v[44:47], v70, s[34:35] offset:2048
	global_load_dwordx4 v[48:51], v70, s[34:35] offset:3072
	s_add_u32 s34, s34, 0x800000
	s_addc_u32 s35, s35, 0
	s_waitcnt vmcnt(16)
	v_mul_f32_e32 v72, v52, v52
	v_mul_f32_e32 v73, v53, v53
	v_fmac_f32_e32 v72, v54, v54
	v_fmac_f32_e32 v73, v55, v55
	v_fmac_f32_e32 v72, v56, v56
	v_fmac_f32_e32 v73, v57, v57
	v_fmac_f32_e32 v72, v58, v58
	v_fmac_f32_e32 v73, v59, v59
	v_fmac_f32_e32 v72, v60, v60
	v_fmac_f32_e32 v73, v61, v61
	v_fmac_f32_e32 v72, v62, v62
	v_fmac_f32_e32 v73, v63, v63
	v_fmac_f32_e32 v72, v64, v64
	v_fmac_f32_e32 v73, v65, v65
	v_fmac_f32_e32 v72, v66, v66
	v_fmac_f32_e32 v73, v67, v67
	v_add_f32_e32 v72, v72, v73
	s_nop 1
	v_add_f32_dpp v72, v72, v72 quad_perm:[1,0,3,2] row_mask:0xf bank_mask:0xf
	s_nop 1
	v_add_f32_dpp v72, v72, v72 quad_perm:[2,3,0,1] row_mask:0xf bank_mask:0xf
	s_nop 1
	v_add_f32_dpp v72, v72, v72 row_half_mirror row_mask:0xf bank_mask:0xf
	s_nop 1
	v_add_f32_dpp v72, v72, v72 row_mirror row_mask:0xf bank_mask:0xf
	s_nop 1
	v_add_f32_dpp v72, v72, v72 row_bcast:15 row_mask:0xa bank_mask:0xf
	s_nop 1
	v_add_f32_dpp v72, v72, v72 row_bcast:31 row_mask:0xc bank_mask:0xf
	s_nop 1
	v_readlane_b32 s43, v72, 63
	s_nop 1
	v_mov_b32_e32 v72, s43
	v_fmamk_f32 v72, v72, 0x3a800000, v82
	v_rsq_f32_e32 v72, v72
	s_nop 0
	v_mul_f32_e32 v52, v52, v72
	v_mul_f32_e32 v53, v53, v72
	v_mul_f32_e32 v54, v54, v72
	v_mul_f32_e32 v55, v55, v72
	v_mul_f32_e32 v52, v4, v52
	v_mul_f32_e32 v53, v5, v53
	v_mul_f32_e32 v54, v6, v54
	v_mul_f32_e32 v55, v7, v55
	v_cvt_pk_bf16_f32 v74, v52, v53
	v_cvt_pk_bf16_f32 v75, v54, v55
	global_store_dwordx2 v71, v[74:75], s[36:37]
	v_mul_f32_e32 v56, v56, v72
	v_mul_f32_e32 v57, v57, v72
	v_mul_f32_e32 v58, v58, v72
	v_mul_f32_e32 v59, v59, v72
	v_mul_f32_e32 v56, v8, v56
	v_mul_f32_e32 v57, v9, v57
	v_mul_f32_e32 v58, v10, v58
	v_mul_f32_e32 v59, v11, v59
	v_cvt_pk_bf16_f32 v76, v56, v57
	v_cvt_pk_bf16_f32 v77, v58, v59
	global_store_dwordx2 v71, v[76:77], s[36:37] offset:512
	v_mul_f32_e32 v60, v60, v72
	v_mul_f32_e32 v61, v61, v72
	v_mul_f32_e32 v62, v62, v72
	v_mul_f32_e32 v63, v63, v72
	v_mul_f32_e32 v60, v12, v60
	v_mul_f32_e32 v61, v13, v61
	v_mul_f32_e32 v62, v14, v62
	v_mul_f32_e32 v63, v15, v63
	v_cvt_pk_bf16_f32 v78, v60, v61
	v_cvt_pk_bf16_f32 v79, v62, v63
	global_store_dwordx2 v71, v[78:79], s[36:37] offset:1024
	v_mul_f32_e32 v64, v64, v72
	v_mul_f32_e32 v65, v65, v72
	v_mul_f32_e32 v66, v66, v72
	v_mul_f32_e32 v67, v67, v72
	v_mul_f32_e32 v64, v16, v64
	v_mul_f32_e32 v65, v17, v65
	v_mul_f32_e32 v66, v18, v66
	v_mul_f32_e32 v67, v19, v67
	v_cvt_pk_bf16_f32 v80, v64, v65
	v_cvt_pk_bf16_f32 v81, v66, v67
	global_store_dwordx2 v71, v[80:81], s[36:37] offset:1536
	s_add_u32 s36, s36, 0x400000
	s_addc_u32 s37, s37, 0
	s_cmpk_lt_u32 s40, 0x100
	s_cbranch_scc0 .Lnrm_p0_nol8
	s_lshl_b32 s42, s40, 12
	s_add_u32 s34, s30, s42
	s_addc_u32 s35, s31, 0
	global_load_dwordx4 v[52:55], v70, s[34:35]
	global_load_dwordx4 v[56:59], v70, s[34:35] offset:1024
	global_load_dwordx4 v[60:63], v70, s[34:35] offset:2048
	global_load_dwordx4 v[64:67], v70, s[34:35] offset:3072
	s_add_u32 s34, s34, 0x800000
	s_addc_u32 s35, s35, 0
.Lnrm_p0_nol8:
	s_waitcnt vmcnt(12)
	v_mul_f32_e32 v72, v20, v20
	v_mul_f32_e32 v73, v21, v21
	v_fmac_f32_e32 v72, v22, v22
	v_fmac_f32_e32 v73, v23, v23
	v_fmac_f32_e32 v72, v24, v24
	v_fmac_f32_e32 v73, v25, v25
	v_fmac_f32_e32 v72, v26, v26
	v_fmac_f32_e32 v73, v27, v27
	v_fmac_f32_e32 v72, v28, v28
	v_fmac_f32_e32 v73, v29, v29
	v_fmac_f32_e32 v72, v30, v30
	v_fmac_f32_e32 v73, v31, v31
	v_fmac_f32_e32 v72, v32, v32
	v_fmac_f32_e32 v73, v33, v33
	v_fmac_f32_e32 v72, v34, v34
	v_fmac_f32_e32 v73, v35, v35
	v_add_f32_e32 v72, v72, v73
	s_nop 1
	v_add_f32_dpp v72, v72, v72 quad_perm:[1,0,3,2] row_mask:0xf bank_mask:0xf
	s_nop 1
	v_add_f32_dpp v72, v72, v72 quad_perm:[2,3,0,1] row_mask:0xf bank_mask:0xf
	s_nop 1
	v_add_f32_dpp v72, v72, v72 row_half_mirror row_mask:0xf bank_mask:0xf
	s_nop 1
	v_add_f32_dpp v72, v72, v72 row_mirror row_mask:0xf bank_mask:0xf
	s_nop 1
	v_add_f32_dpp v72, v72, v72 row_bcast:15 row_mask:0xa bank_mask:0xf
	s_nop 1
	v_add_f32_dpp v72, v72, v72 row_bcast:31 row_mask:0xc bank_mask:0xf
	s_nop 1
	v_readlane_b32 s43, v72, 63
	s_nop 1
	v_mov_b32_e32 v72, s43
	v_fmamk_f32 v72, v72, 0x3a800000, v82
	v_rsq_f32_e32 v72, v72
	s_nop 0
	v_mul_f32_e32 v20, v20, v72
	v_mul_f32_e32 v21, v21, v72
	v_mul_f32_e32 v22, v22, v72
	v_mul_f32_e32 v23, v23, v72
	v_mul_f32_e32 v20, v4, v20
	v_mul_f32_e32 v21, v5, v21
	v_mul_f32_e32 v22, v6, v22
	v_mul_f32_e32 v23, v7, v23
	v_cvt_pk_bf16_f32 v74, v20, v21
	v_cvt_pk_bf16_f32 v75, v22, v23
	global_store_dwordx2 v71, v[74:75], s[36:37]
	v_mul_f32_e32 v24, v24, v72
	v_mul_f32_e32 v25, v25, v72
	v_mul_f32_e32 v26, v26, v72
	v_mul_f32_e32 v27, v27, v72
	v_mul_f32_e32 v24, v8, v24
	v_mul_f32_e32 v25, v9, v25
	v_mul_f32_e32 v26, v10, v26
	v_mul_f32_e32 v27, v11, v27
	v_cvt_pk_bf16_f32 v76, v24, v25
	v_cvt_pk_bf16_f32 v77, v26, v27
	global_store_dwordx2 v71, v[76:77], s[36:37] offset:512
	v_mul_f32_e32 v28, v28, v72
	v_mul_f32_e32 v29, v29, v72
	v_mul_f32_e32 v30, v30, v72
	v_mul_f32_e32 v31, v31, v72
	v_mul_f32_e32 v28, v12, v28
	v_mul_f32_e32 v29, v13, v29
	v_mul_f32_e32 v30, v14, v30
	v_mul_f32_e32 v31, v15, v31
	v_cvt_pk_bf16_f32 v78, v28, v29
	v_cvt_pk_bf16_f32 v79, v30, v31
	global_store_dwordx2 v71, v[78:79], s[36:37] offset:1024
	v_mul_f32_e32 v32, v32, v72
	v_mul_f32_e32 v33, v33, v72
	v_mul_f32_e32 v34, v34, v72
	v_mul_f32_e32 v35, v35, v72
	v_mul_f32_e32 v32, v16, v32
	v_mul_f32_e32 v33, v17, v33
	v_mul_f32_e32 v34, v18, v34
	v_mul_f32_e32 v35, v19, v35
	v_cvt_pk_bf16_f32 v80, v32, v33
	v_cvt_pk_bf16_f32 v81, v34, v35
	global_store_dwordx2 v71, v[80:81], s[36:37] offset:1536
	s_add_u32 s36, s36, 0x400000
	s_addc_u32 s37, s37, 0
	s_waitcnt vmcnt(8)
	v_mul_f32_e32 v72, v36, v36
	v_mul_f32_e32 v73, v37, v37
	v_fmac_f32_e32 v72, v38, v38
	v_fmac_f32_e32 v73, v39, v39
	v_fmac_f32_e32 v72, v40, v40
	v_fmac_f32_e32 v73, v41, v41
	v_fmac_f32_e32 v72, v42, v42
	v_fmac_f32_e32 v73, v43, v43
	v_fmac_f32_e32 v72, v44, v44
	v_fmac_f32_e32 v73, v45, v45
	v_fmac_f32_e32 v72, v46, v46
	v_fmac_f32_e32 v73, v47, v47
	v_fmac_f32_e32 v72, v48, v48
	v_fmac_f32_e32 v73, v49, v49
	v_fmac_f32_e32 v72, v50, v50
	v_fmac_f32_e32 v73, v51, v51
	v_add_f32_e32 v72, v72, v73
	s_nop 1
	v_add_f32_dpp v72, v72, v72 quad_perm:[1,0,3,2] row_mask:0xf bank_mask:0xf
	s_nop 1
	v_add_f32_dpp v72, v72, v72 quad_perm:[2,3,0,1] row_mask:0xf bank_mask:0xf
	s_nop 1
	v_add_f32_dpp v72, v72, v72 row_half_mirror row_mask:0xf bank_mask:0xf
	s_nop 1
	v_add_f32_dpp v72, v72, v72 row_mirror row_mask:0xf bank_mask:0xf
	s_nop 1
	v_add_f32_dpp v72, v72, v72 row_bcast:15 row_mask:0xa bank_mask:0xf
	s_nop 1
	v_add_f32_dpp v72, v72, v72 row_bcast:31 row_mask:0xc bank_mask:0xf
	s_nop 1
	v_readlane_b32 s43, v72, 63
	s_nop 1
	v_mov_b32_e32 v72, s43
	v_fmamk_f32 v72, v72, 0x3a800000, v82
	v_rsq_f32_e32 v72, v72
	s_nop 0
	v_mul_f32_e32 v36, v36, v72
	v_mul_f32_e32 v37, v37, v72
	v_mul_f32_e32 v38, v38, v72
	v_mul_f32_e32 v39, v39, v72
	v_mul_f32_e32 v36, v4, v36
	v_mul_f32_e32 v37, v5, v37
	v_mul_f32_e32 v38, v6, v38
	v_mul_f32_e32 v39, v7, v39
	v_cvt_pk_bf16_f32 v74, v36, v37
	v_cvt_pk_bf16_f32 v75, v38, v39
	global_store_dwordx2 v71, v[74:75], s[36:37]
	v_mul_f32_e32 v40, v40, v72
	v_mul_f32_e32 v41, v41, v72
	v_mul_f32_e32 v42, v42, v72
	v_mul_f32_e32 v43, v43, v72
	v_mul_f32_e32 v40, v8, v40
	v_mul_f32_e32 v41, v9, v41
	v_mul_f32_e32 v42, v10, v42
	v_mul_f32_e32 v43, v11, v43
	v_cvt_pk_bf16_f32 v76, v40, v41
	v_cvt_pk_bf16_f32 v77, v42, v43
	global_store_dwordx2 v71, v[76:77], s[36:37] offset:512
	v_mul_f32_e32 v44, v44, v72
	v_mul_f32_e32 v45, v45, v72
	v_mul_f32_e32 v46, v46, v72
	v_mul_f32_e32 v47, v47, v72
	v_mul_f32_e32 v44, v12, v44
	v_mul_f32_e32 v45, v13, v45
	v_mul_f32_e32 v46, v14, v46
	v_mul_f32_e32 v47, v15, v47
	v_cvt_pk_bf16_f32 v78, v44, v45
	v_cvt_pk_bf16_f32 v79, v46, v47
	global_store_dwordx2 v71, v[78:79], s[36:37] offset:1024
	v_mul_f32_e32 v48, v48, v72
	v_mul_f32_e32 v49, v49, v72
	v_mul_f32_e32 v50, v50, v72
	v_mul_f32_e32 v51, v51, v72
	v_mul_f32_e32 v48, v16, v48
	v_mul_f32_e32 v49, v17, v49
	v_mul_f32_e32 v50, v18, v50
	v_mul_f32_e32 v51, v19, v51
	v_cvt_pk_bf16_f32 v80, v48, v49
	v_cvt_pk_bf16_f32 v81, v50, v51
	global_store_dwordx2 v71, v[80:81], s[36:37] offset:1536
	s_add_u32 s36, s36, 0x400000
	s_addc_u32 s37, s37, 0
	s_cmpk_lt_u32 s40, 0x100
	s_cbranch_scc0 .Lnrm_p0_done
	s_waitcnt vmcnt(8)
	v_mul_f32_e32 v72, v52, v52
	v_mul_f32_e32 v73, v53, v53
	v_fmac_f32_e32 v72, v54, v54
	v_fmac_f32_e32 v73, v55, v55
	v_fmac_f32_e32 v72, v56, v56
	v_fmac_f32_e32 v73, v57, v57
	v_fmac_f32_e32 v72, v58, v58
	v_fmac_f32_e32 v73, v59, v59
	v_fmac_f32_e32 v72, v60, v60
	v_fmac_f32_e32 v73, v61, v61
	v_fmac_f32_e32 v72, v62, v62
	v_fmac_f32_e32 v73, v63, v63
	v_fmac_f32_e32 v72, v64, v64
	v_fmac_f32_e32 v73, v65, v65
	v_fmac_f32_e32 v72, v66, v66
	v_fmac_f32_e32 v73, v67, v67
	v_add_f32_e32 v72, v72, v73
	s_nop 1
	v_add_f32_dpp v72, v72, v72 quad_perm:[1,0,3,2] row_mask:0xf bank_mask:0xf
	s_nop 1
	v_add_f32_dpp v72, v72, v72 quad_perm:[2,3,0,1] row_mask:0xf bank_mask:0xf
	s_nop 1
	v_add_f32_dpp v72, v72, v72 row_half_mirror row_mask:0xf bank_mask:0xf
	s_nop 1
	v_add_f32_dpp v72, v72, v72 row_mirror row_mask:0xf bank_mask:0xf
	s_nop 1
	v_add_f32_dpp v72, v72, v72 row_bcast:15 row_mask:0xa bank_mask:0xf
	s_nop 1
	v_add_f32_dpp v72, v72, v72 row_bcast:31 row_mask:0xc bank_mask:0xf
	s_nop 1
	v_readlane_b32 s43, v72, 63
	s_nop 1
	v_mov_b32_e32 v72, s43
	v_fmamk_f32 v72, v72, 0x3a800000, v82
	v_rsq_f32_e32 v72, v72
	s_nop 0
	v_mul_f32_e32 v52, v52, v72
	v_mul_f32_e32 v53, v53, v72
	v_mul_f32_e32 v54, v54, v72
	v_mul_f32_e32 v55, v55, v72
	v_mul_f32_e32 v52, v4, v52
	v_mul_f32_e32 v53, v5, v53
	v_mul_f32_e32 v54, v6, v54
	v_mul_f32_e32 v55, v7, v55
	v_cvt_pk_bf16_f32 v74, v52, v53
	v_cvt_pk_bf16_f32 v75, v54, v55
	global_store_dwordx2 v71, v[74:75], s[36:37]
	v_mul_f32_e32 v56, v56, v72
	v_mul_f32_e32 v57, v57, v72
	v_mul_f32_e32 v58, v58, v72
	v_mul_f32_e32 v59, v59, v72
	v_mul_f32_e32 v56, v8, v56
	v_mul_f32_e32 v57, v9, v57
	v_mul_f32_e32 v58, v10, v58
	v_mul_f32_e32 v59, v11, v59
	v_cvt_pk_bf16_f32 v76, v56, v57
	v_cvt_pk_bf16_f32 v77, v58, v59
	global_store_dwordx2 v71, v[76:77], s[36:37] offset:512
	v_mul_f32_e32 v60, v60, v72
	v_mul_f32_e32 v61, v61, v72
	v_mul_f32_e32 v62, v62, v72
	v_mul_f32_e32 v63, v63, v72
	v_mul_f32_e32 v60, v12, v60
	v_mul_f32_e32 v61, v13, v61
	v_mul_f32_e32 v62, v14, v62
	v_mul_f32_e32 v63, v15, v63
	v_cvt_pk_bf16_f32 v78, v60, v61
	v_cvt_pk_bf16_f32 v79, v62, v63
	global_store_dwordx2 v71, v[78:79], s[36:37] offset:1024
	v_mul_f32_e32 v64, v64, v72
	v_mul_f32_e32 v65, v65, v72
	v_mul_f32_e32 v66, v66, v72
	v_mul_f32_e32 v67, v67, v72
	v_mul_f32_e32 v64, v16, v64
	v_mul_f32_e32 v65, v17, v65
	v_mul_f32_e32 v66, v18, v66
	v_mul_f32_e32 v67, v19, v67
	v_cvt_pk_bf16_f32 v80, v64, v65
	v_cvt_pk_bf16_f32 v81, v66, v67
	global_store_dwordx2 v71, v[80:81], s[36:37] offset:1536
	s_add_u32 s36, s36, 0x400000
	s_addc_u32 s37, s37, 0
.Lnrm_p0_done:
	v_mbcnt_lo_u32_b32 v30, -1, 0
	s_mov_b64 s[8:9], exec
	s_branch .LBB0_85
.Lnrm_p0_orig:
	v_add_u32_e32 v16, s4, v1
	s_movk_i32 s4, 0x4100
	v_cmp_gt_i32_e32 vcc, s4, v16
	v_mbcnt_lo_u32_b32 v30, -1, 0
	s_and_saveexec_b64 s[8:9], vcc
	s_cbranch_execz .LBB0_85
	s_load_dwordx2 s[4:5], s[2:3], 0x48
	v_lshlrev_b32_e32 v0, 2, v0
	v_and_b32_e32 v24, 0xfc, v0
	v_lshlrev_b32_e32 v17, 2, v24
	s_lshl_b32 s10, s18, 2
	s_waitcnt lgkmcnt(0)
	global_load_dwordx4 v[0:3], v17, s[4:5]
	global_load_dwordx4 v[4:7], v17, s[4:5] offset:1024
	global_load_dwordx4 v[8:11], v17, s[4:5] offset:2048
	global_load_dwordx4 v[12:15], v17, s[4:5] offset:3072
	v_mbcnt_hi_u32_b32 v17, -1, v30
	v_and_b32_e32 v18, 64, v17
	v_add_u32_e32 v18, 64, v18
	v_xor_b32_e32 v20, 1, v17
	v_cmp_lt_i32_e32 vcc, v20, v18
	s_load_dwordx4 s[4:7], s[2:3], 0x0
	s_load_dwordx2 s[12:13], s[2:3], 0x138
	v_cndmask_b32_e32 v20, v17, v20, vcc
	v_lshlrev_b32_e32 v31, 2, v20
	v_xor_b32_e32 v20, 2, v17
	v_cmp_lt_i32_e32 vcc, v20, v18
	v_mov_b32_e32 v19, 0
	s_ashr_i32 s11, s10, 31
	v_cndmask_b32_e32 v20, v17, v20, vcc
	v_lshlrev_b32_e32 v32, 2, v20
	v_xor_b32_e32 v20, 4, v17
	v_cmp_lt_i32_e32 vcc, v20, v18
	s_movk_i32 s14, 0x3fff
	v_mov_b32_e32 v25, v19
	v_cndmask_b32_e32 v20, v17, v20, vcc
	v_lshlrev_b32_e32 v33, 2, v20
	v_xor_b32_e32 v20, 8, v17
	v_cmp_lt_i32_e32 vcc, v20, v18
	v_mov_b32_e32 v37, 0x358637bd
	s_mov_b32 s15, 0x800000
	v_cndmask_b32_e32 v20, v17, v20, vcc
	v_lshlrev_b32_e32 v34, 2, v20
	v_xor_b32_e32 v20, 16, v17
	v_cmp_lt_i32_e32 vcc, v20, v18
	s_movk_i32 s16, 0x40ff
	s_nop 0
	v_cndmask_b32_e32 v20, v17, v20, vcc
	v_lshlrev_b32_e32 v35, 2, v20
	v_xor_b32_e32 v20, 32, v17
	v_cmp_lt_i32_e32 vcc, v20, v18
	v_lshlrev_b32_e32 v18, 1, v24
	v_lshlrev_b32_e32 v24, 2, v24
	v_cndmask_b32_e32 v17, v17, v20, vcc
	v_lshlrev_b32_e32 v36, 2, v17
	v_ashrrev_i32_e32 v17, 31, v16
	v_lshlrev_b64 v[22:23], 12, v[16:17]
	s_waitcnt lgkmcnt(0)
	v_lshl_add_u64 v[20:21], s[12:13], 0, v[18:19]
	v_lshl_add_u64 v[22:23], s[4:5], 0, v[22:23]
	s_lshl_b64 s[4:5], s[10:11], 12
	s_mov_b64 s[12:13], 0
	s_branch .LBB0_83
